# uq (q_nope) and ukv (k_nope) epilogues: norm gains loaded once per tile instead of per row, serialized load/store round trips removed, on top of v17
# speedup vs baseline: 1.0209x; 1.0113x over previous
.LBB0_276:
	s_or_b64 exec, exec, s[0:1]
	s_add_i32 s4, 0, 0x20000
	s_waitcnt lgkmcnt(0)
	s_barrier
	v_add_u32_e32 v2, s4, v177
	ds_read_b128 v[6:9], v2
	s_waitcnt lgkmcnt(1)
	ds_read_b128 v[2:5], v2 offset:16
	v_lshl_add_u32 v38, v185, 3, s73
	v_ashrrev_i32_e32 v39, 31, v38
	s_lshl_b64 s[10:11], s[68:69], 20
	s_waitcnt lgkmcnt(1)
	v_mov_b32_e32 v18, v7
	v_mov_b32_e32 v19, v8
	v_mov_b32_e32 v7, v9
	v_pk_add_f32 v[6:7], v[18:19], v[6:7]
	s_lshl_b32 s0, s83, 8
	v_add_f32_e32 v6, v6, v7
	v_fmamk_f32 v6, v6, 0x3c000000, v243
	v_lshlrev_b64 v[168:169], 12, v[168:169]
	s_nop 1
	v_readlane_b32 s6, v251, 45
	v_readlane_b32 s7, v251, 46
	s_add_u32 s44, s6, s10
	v_rsq_f32_e32 v6, v6
	s_nop 0
	v_lshl_add_u64 v[18:19], v[38:39], 2, s[56:57]
	v_mul_f32_e32 v186, 0x3dd53b94, v6
	global_load_dwordx4 v[212:215], v[18:19], off
	global_load_dwordx4 v[216:219], v[18:19], off offset:16
	s_addc_u32 s45, s7, s11
	s_ashr_i32 s1, s0, 31
	s_lshl_b64 s[68:69], s[0:1], 1
	v_lshlrev_b64 v[38:39], 1, v[38:39]
	s_waitcnt vmcnt(0)
	v_pk_mul_f32 v[8:9], v[164:165], v[218:219]
	v_pk_mul_f32 v[160:161], v[160:161], v[214:215]
	v_pk_mul_f32 v[6:7], v[166:167], v[216:217]
	v_pk_mul_f32 v[160:161], v[160:161], v[186:187] op_sel_hi:[1,0]
	v_pk_mul_f32 v[162:163], v[162:163], v[212:213]
	v_pk_mul_f32 v[164:165], v[8:9], v[186:187] op_sel_hi:[1,0]
	v_pk_mul_f32 v[8:9], v[6:7], v[186:187] op_sel_hi:[1,0]
	v_cvt_pk_bf16_f32 v7, v160, v161
	v_lshl_add_u64 v[160:161], s[44:45], 0, v[168:169]
	v_pk_mul_f32 v[162:163], v[162:163], v[186:187] op_sel_hi:[1,0]
	v_lshl_add_u64 v[160:161], v[160:161], 0, s[68:69]
	v_cvt_pk_bf16_f32 v6, v162, v163
	v_cvt_pk_bf16_f32 v8, v8, v9
	v_cvt_pk_bf16_f32 v9, v164, v165
	v_lshl_add_u64 v[160:161], v[160:161], 0, v[38:39]
	global_store_dwordx4 v[160:161], v[6:9], off
	s_nop 1
	s_waitcnt lgkmcnt(0)
	s_nop 0
	v_mov_b32_e32 v6, v3
	v_mov_b32_e32 v7, v4
	v_mov_b32_e32 v3, v5
	v_pk_add_f32 v[2:3], v[6:7], v[2:3]
	s_nop 0
	v_add_f32_e32 v2, v2, v3
	v_fmamk_f32 v2, v2, 0x3c000000, v243
	v_rsq_f32_e32 v2, v2
	s_nop 0
	v_mul_f32_e32 v6, 0x3dd53b94, v2
	v_pk_mul_f32 v[4:5], v[150:151], v[218:219]
	v_pk_mul_f32 v[8:9], v[156:157], v[214:215]
	v_pk_mul_f32 v[156:157], v[158:159], v[212:213]
	v_pk_mul_f32 v[2:3], v[152:153], v[216:217]
	v_pk_mul_f32 v[8:9], v[8:9], v[6:7] op_sel_hi:[1,0]
	v_pk_mul_f32 v[156:157], v[156:157], v[6:7] op_sel_hi:[1,0]
	v_pk_mul_f32 v[150:151], v[4:5], v[6:7] op_sel_hi:[1,0]
	v_pk_mul_f32 v[4:5], v[2:3], v[6:7] op_sel_hi:[1,0]
	v_cvt_pk_bf16_f32 v2, v156, v157
	v_cvt_pk_bf16_f32 v3, v8, v9
	v_cvt_pk_bf16_f32 v4, v4, v5
	v_cvt_pk_bf16_f32 v5, v150, v151
	global_store_dwordx4 v[160:161], v[2:5], off offset:256
	s_nop 1
	v_lshlrev_b64 v[150:151], 12, v[154:155]
	s_nop 0
	v_add_u32_e32 v2, s4, v176
	ds_read_b128 v[6:9], v2
	ds_read_b128 v[2:5], v2 offset:16
	s_waitcnt lgkmcnt(1)
	v_mov_b32_e32 v152, v7
	v_mov_b32_e32 v153, v8
	v_mov_b32_e32 v7, v9
	v_pk_add_f32 v[6:7], v[152:153], v[6:7]
	s_nop 0
	v_add_f32_e32 v6, v6, v7
	v_fmamk_f32 v6, v6, 0x3c000000, v243
	v_rsq_f32_e32 v6, v6
	s_nop 0
	v_mul_f32_e32 v156, 0x3dd53b94, v6
	v_pk_mul_f32 v[8:9], v[134:135], v[218:219]
	v_pk_mul_f32 v[130:131], v[130:131], v[214:215]
	v_pk_mul_f32 v[6:7], v[136:137], v[216:217]
	v_pk_mul_f32 v[130:131], v[130:131], v[156:157] op_sel_hi:[1,0]
	v_pk_mul_f32 v[132:133], v[132:133], v[212:213]
	v_pk_mul_f32 v[134:135], v[8:9], v[156:157] op_sel_hi:[1,0]
	v_pk_mul_f32 v[8:9], v[6:7], v[156:157] op_sel_hi:[1,0]
	v_cvt_pk_bf16_f32 v7, v130, v131
	v_lshl_add_u64 v[130:131], s[44:45], 0, v[150:151]
	v_pk_mul_f32 v[132:133], v[132:133], v[156:157] op_sel_hi:[1,0]
	v_lshl_add_u64 v[130:131], v[130:131], 0, s[68:69]
	v_cvt_pk_bf16_f32 v6, v132, v133
	v_cvt_pk_bf16_f32 v8, v8, v9
	v_cvt_pk_bf16_f32 v9, v134, v135
	v_lshl_add_u64 v[130:131], v[130:131], 0, v[38:39]
	global_store_dwordx4 v[130:131], v[6:9], off
	s_nop 1
	s_waitcnt lgkmcnt(0)
	s_nop 0
	v_mov_b32_e32 v6, v3
	v_mov_b32_e32 v7, v4
	v_mov_b32_e32 v3, v5
	v_pk_add_f32 v[2:3], v[6:7], v[2:3]
	s_nop 0
	v_add_f32_e32 v2, v2, v3
	v_fmamk_f32 v2, v2, 0x3c000000, v243
	v_rsq_f32_e32 v2, v2
	s_nop 0
	v_mul_f32_e32 v6, 0x3dd53b94, v2
	v_pk_mul_f32 v[4:5], v[120:121], v[218:219]
	v_pk_mul_f32 v[8:9], v[126:127], v[214:215]
	v_pk_mul_f32 v[126:127], v[128:129], v[212:213]
	v_pk_mul_f32 v[2:3], v[122:123], v[216:217]
	v_pk_mul_f32 v[8:9], v[8:9], v[6:7] op_sel_hi:[1,0]
	v_pk_mul_f32 v[126:127], v[126:127], v[6:7] op_sel_hi:[1,0]
	v_pk_mul_f32 v[120:121], v[4:5], v[6:7] op_sel_hi:[1,0]
	v_pk_mul_f32 v[4:5], v[2:3], v[6:7] op_sel_hi:[1,0]
	v_cvt_pk_bf16_f32 v2, v126, v127
	v_cvt_pk_bf16_f32 v3, v8, v9
	v_cvt_pk_bf16_f32 v4, v4, v5
	v_cvt_pk_bf16_f32 v5, v120, v121
	v_add_u32_e32 v123, s4, v175
	global_store_dwordx4 v[130:131], v[2:5], off offset:256
	s_nop 1
	ds_read_b128 v[2:5], v123
	v_lshlrev_b64 v[120:121], 12, v[124:125]
	s_waitcnt lgkmcnt(0)
	v_mov_b32_e32 v6, v3
	v_mov_b32_e32 v7, v4
	v_mov_b32_e32 v3, v5
	v_pk_add_f32 v[2:3], v[6:7], v[2:3]
	s_nop 0
	v_add_f32_e32 v2, v2, v3
	v_fmamk_f32 v2, v2, 0x3c000000, v243
	v_rsq_f32_e32 v2, v2
	s_nop 0
	v_mul_f32_e32 v122, 0x3dd53b94, v2
	v_pk_mul_f32 v[4:5], v[116:117], v[218:219]
	v_pk_mul_f32 v[6:7], v[114:115], v[212:213]
	v_pk_mul_f32 v[2:3], v[118:119], v[216:217]
	v_pk_mul_f32 v[6:7], v[6:7], v[122:123] op_sel_hi:[1,0]
	v_pk_mul_f32 v[8:9], v[112:113], v[214:215]
	v_pk_mul_f32 v[112:113], v[4:5], v[122:123] op_sel_hi:[1,0]
	v_pk_mul_f32 v[4:5], v[2:3], v[122:123] op_sel_hi:[1,0]
	v_cvt_pk_bf16_f32 v2, v6, v7
	v_lshl_add_u64 v[6:7], s[44:45], 0, v[120:121]
	v_pk_mul_f32 v[8:9], v[8:9], v[122:123] op_sel_hi:[1,0]
	v_lshl_add_u64 v[6:7], v[6:7], 0, s[68:69]
	v_cvt_pk_bf16_f32 v3, v8, v9
	v_cvt_pk_bf16_f32 v4, v4, v5
	v_cvt_pk_bf16_f32 v5, v112, v113
	v_lshl_add_u64 v[6:7], v[6:7], 0, v[38:39]
	global_store_dwordx4 v[6:7], v[2:5], off
	s_nop 1
	ds_read_b128 v[2:5], v123 offset:16
	s_waitcnt lgkmcnt(0)
	v_mov_b32_e32 v8, v3
	v_mov_b32_e32 v9, v4
	v_mov_b32_e32 v3, v5
	v_pk_add_f32 v[2:3], v[8:9], v[2:3]
	s_nop 0
	v_add_f32_e32 v2, v2, v3
	v_fmamk_f32 v2, v2, 0x3c000000, v243
	v_rsq_f32_e32 v2, v2
	s_nop 0
	v_mul_f32_e32 v8, 0x3dd53b94, v2
	v_pk_mul_f32 v[4:5], v[102:103], v[218:219]
	v_pk_mul_f32 v[108:109], v[108:109], v[214:215]
	v_pk_mul_f32 v[110:111], v[110:111], v[212:213]
	v_pk_mul_f32 v[2:3], v[104:105], v[216:217]
	v_pk_mul_f32 v[108:109], v[108:109], v[8:9] op_sel_hi:[1,0]
	v_pk_mul_f32 v[110:111], v[110:111], v[8:9] op_sel_hi:[1,0]
	v_pk_mul_f32 v[102:103], v[4:5], v[8:9] op_sel_hi:[1,0]
	v_pk_mul_f32 v[4:5], v[2:3], v[8:9] op_sel_hi:[1,0]
	v_cvt_pk_bf16_f32 v2, v110, v111
	v_cvt_pk_bf16_f32 v3, v108, v109
	v_cvt_pk_bf16_f32 v4, v4, v5
	v_cvt_pk_bf16_f32 v5, v102, v103
	v_add_u32_e32 v105, s4, v174
	global_store_dwordx4 v[6:7], v[2:5], off offset:256
	s_nop 1
	ds_read_b128 v[2:5], v105
	v_lshlrev_b64 v[102:103], 12, v[106:107]
	s_waitcnt lgkmcnt(0)
	v_mov_b32_e32 v6, v3
	v_mov_b32_e32 v7, v4
	v_mov_b32_e32 v3, v5
	v_pk_add_f32 v[2:3], v[6:7], v[2:3]
	s_nop 0
	v_add_f32_e32 v2, v2, v3
	v_fmamk_f32 v2, v2, 0x3c000000, v243
	v_rsq_f32_e32 v2, v2
	s_nop 0
	v_mul_f32_e32 v104, 0x3dd53b94, v2
	v_pk_mul_f32 v[4:5], v[98:99], v[218:219]
	v_pk_mul_f32 v[6:7], v[96:97], v[212:213]
	v_pk_mul_f32 v[2:3], v[100:101], v[216:217]
	v_pk_mul_f32 v[6:7], v[6:7], v[104:105] op_sel_hi:[1,0]
	v_pk_mul_f32 v[8:9], v[94:95], v[214:215]
	v_pk_mul_f32 v[94:95], v[4:5], v[104:105] op_sel_hi:[1,0]
	v_pk_mul_f32 v[4:5], v[2:3], v[104:105] op_sel_hi:[1,0]
	v_cvt_pk_bf16_f32 v2, v6, v7
	v_lshl_add_u64 v[6:7], s[44:45], 0, v[102:103]
	v_pk_mul_f32 v[8:9], v[8:9], v[104:105] op_sel_hi:[1,0]
	v_lshl_add_u64 v[6:7], v[6:7], 0, s[68:69]
	v_cvt_pk_bf16_f32 v3, v8, v9
	v_cvt_pk_bf16_f32 v4, v4, v5
	v_cvt_pk_bf16_f32 v5, v94, v95
	v_lshl_add_u64 v[6:7], v[6:7], 0, v[38:39]
	global_store_dwordx4 v[6:7], v[2:5], off
	s_nop 1
	ds_read_b128 v[2:5], v105 offset:16
	s_waitcnt lgkmcnt(0)
	v_mov_b32_e32 v8, v3
	v_mov_b32_e32 v9, v4
	v_mov_b32_e32 v3, v5
	v_pk_add_f32 v[2:3], v[8:9], v[2:3]
	s_nop 0
	v_add_f32_e32 v2, v2, v3
	v_fmamk_f32 v2, v2, 0x3c000000, v243
	v_rsq_f32_e32 v2, v2
	s_nop 0
	v_mul_f32_e32 v8, 0x3dd53b94, v2
	v_pk_mul_f32 v[4:5], v[84:85], v[218:219]
	v_pk_mul_f32 v[90:91], v[90:91], v[214:215]
	v_pk_mul_f32 v[92:93], v[92:93], v[212:213]
	v_pk_mul_f32 v[2:3], v[86:87], v[216:217]
	v_pk_mul_f32 v[90:91], v[90:91], v[8:9] op_sel_hi:[1,0]
	v_pk_mul_f32 v[92:93], v[92:93], v[8:9] op_sel_hi:[1,0]
	v_pk_mul_f32 v[84:85], v[4:5], v[8:9] op_sel_hi:[1,0]
	v_pk_mul_f32 v[4:5], v[2:3], v[8:9] op_sel_hi:[1,0]
	v_cvt_pk_bf16_f32 v2, v92, v93
	v_cvt_pk_bf16_f32 v3, v90, v91
	v_cvt_pk_bf16_f32 v4, v4, v5
	v_cvt_pk_bf16_f32 v5, v84, v85
	v_add_u32_e32 v87, s4, v173
	global_store_dwordx4 v[6:7], v[2:5], off offset:256
	s_nop 1
	ds_read_b128 v[2:5], v87
	v_lshlrev_b64 v[84:85], 12, v[88:89]
	s_waitcnt lgkmcnt(0)
	v_mov_b32_e32 v6, v3
	v_mov_b32_e32 v7, v4
	v_mov_b32_e32 v3, v5
	v_pk_add_f32 v[2:3], v[6:7], v[2:3]
	s_nop 0
	v_add_f32_e32 v2, v2, v3
	v_fmamk_f32 v2, v2, 0x3c000000, v243
	v_rsq_f32_e32 v2, v2
	s_nop 0
	v_mul_f32_e32 v86, 0x3dd53b94, v2
	v_pk_mul_f32 v[4:5], v[80:81], v[218:219]
	v_pk_mul_f32 v[6:7], v[78:79], v[212:213]
	v_pk_mul_f32 v[2:3], v[82:83], v[216:217]
	v_pk_mul_f32 v[6:7], v[6:7], v[86:87] op_sel_hi:[1,0]
	v_pk_mul_f32 v[8:9], v[76:77], v[214:215]
	v_pk_mul_f32 v[76:77], v[4:5], v[86:87] op_sel_hi:[1,0]
	v_pk_mul_f32 v[4:5], v[2:3], v[86:87] op_sel_hi:[1,0]
	v_cvt_pk_bf16_f32 v2, v6, v7
	v_lshl_add_u64 v[6:7], s[44:45], 0, v[84:85]
	v_pk_mul_f32 v[8:9], v[8:9], v[86:87] op_sel_hi:[1,0]
	v_lshl_add_u64 v[6:7], v[6:7], 0, s[68:69]
	v_cvt_pk_bf16_f32 v3, v8, v9
	v_cvt_pk_bf16_f32 v4, v4, v5
	v_cvt_pk_bf16_f32 v5, v76, v77
	v_lshl_add_u64 v[6:7], v[6:7], 0, v[38:39]
	global_store_dwordx4 v[6:7], v[2:5], off
	s_nop 1
	ds_read_b128 v[2:5], v87 offset:16
	s_waitcnt lgkmcnt(0)
	v_mov_b32_e32 v8, v3
	v_mov_b32_e32 v9, v4
	v_mov_b32_e32 v3, v5
	v_pk_add_f32 v[2:3], v[8:9], v[2:3]
	s_nop 0
	v_add_f32_e32 v2, v2, v3
	v_fmamk_f32 v2, v2, 0x3c000000, v243
	v_rsq_f32_e32 v2, v2
	s_nop 0
	v_mul_f32_e32 v8, 0x3dd53b94, v2
	v_pk_mul_f32 v[4:5], v[66:67], v[218:219]
	v_pk_mul_f32 v[72:73], v[72:73], v[214:215]
	v_pk_mul_f32 v[74:75], v[74:75], v[212:213]
	v_pk_mul_f32 v[2:3], v[68:69], v[216:217]
	v_pk_mul_f32 v[72:73], v[72:73], v[8:9] op_sel_hi:[1,0]
	v_pk_mul_f32 v[74:75], v[74:75], v[8:9] op_sel_hi:[1,0]
	v_pk_mul_f32 v[66:67], v[4:5], v[8:9] op_sel_hi:[1,0]
	v_pk_mul_f32 v[4:5], v[2:3], v[8:9] op_sel_hi:[1,0]
	v_cvt_pk_bf16_f32 v2, v74, v75
	v_cvt_pk_bf16_f32 v3, v72, v73
	v_cvt_pk_bf16_f32 v4, v4, v5
	v_cvt_pk_bf16_f32 v5, v66, v67
	v_add_u32_e32 v69, s4, v172
	global_store_dwordx4 v[6:7], v[2:5], off offset:256
	s_nop 1
	ds_read_b128 v[2:5], v69
	v_lshlrev_b64 v[66:67], 12, v[70:71]
	s_waitcnt lgkmcnt(0)
	v_mov_b32_e32 v6, v3
	v_mov_b32_e32 v7, v4
	v_mov_b32_e32 v3, v5
	v_pk_add_f32 v[2:3], v[6:7], v[2:3]
	s_nop 0
	v_add_f32_e32 v2, v2, v3
	v_fmamk_f32 v2, v2, 0x3c000000, v243
	v_rsq_f32_e32 v2, v2
	s_nop 0
	v_mul_f32_e32 v68, 0x3dd53b94, v2
	v_pk_mul_f32 v[4:5], v[62:63], v[218:219]
	v_pk_mul_f32 v[6:7], v[60:61], v[212:213]
	v_pk_mul_f32 v[2:3], v[64:65], v[216:217]
	v_pk_mul_f32 v[6:7], v[6:7], v[68:69] op_sel_hi:[1,0]
	v_pk_mul_f32 v[8:9], v[58:59], v[214:215]
	v_pk_mul_f32 v[58:59], v[4:5], v[68:69] op_sel_hi:[1,0]
	v_pk_mul_f32 v[4:5], v[2:3], v[68:69] op_sel_hi:[1,0]
	v_cvt_pk_bf16_f32 v2, v6, v7
	v_lshl_add_u64 v[6:7], s[44:45], 0, v[66:67]
	v_pk_mul_f32 v[8:9], v[8:9], v[68:69] op_sel_hi:[1,0]
	v_lshl_add_u64 v[6:7], v[6:7], 0, s[68:69]
	v_cvt_pk_bf16_f32 v3, v8, v9
	v_cvt_pk_bf16_f32 v4, v4, v5
	v_cvt_pk_bf16_f32 v5, v58, v59
	v_lshl_add_u64 v[6:7], v[6:7], 0, v[38:39]
	global_store_dwordx4 v[6:7], v[2:5], off
	s_nop 1
	ds_read_b128 v[2:5], v69 offset:16
	s_waitcnt lgkmcnt(0)
	v_mov_b32_e32 v8, v3
	v_mov_b32_e32 v9, v4
	v_mov_b32_e32 v3, v5
	v_pk_add_f32 v[2:3], v[8:9], v[2:3]
	s_nop 0
	v_add_f32_e32 v2, v2, v3
	v_fmamk_f32 v2, v2, 0x3c000000, v243
	v_rsq_f32_e32 v2, v2
	s_nop 0
	v_mul_f32_e32 v8, 0x3dd53b94, v2
	v_pk_mul_f32 v[4:5], v[48:49], v[218:219]
	v_pk_mul_f32 v[54:55], v[54:55], v[214:215]
	v_pk_mul_f32 v[56:57], v[56:57], v[212:213]
	v_pk_mul_f32 v[2:3], v[50:51], v[216:217]
	v_pk_mul_f32 v[54:55], v[54:55], v[8:9] op_sel_hi:[1,0]
	v_pk_mul_f32 v[56:57], v[56:57], v[8:9] op_sel_hi:[1,0]
	v_pk_mul_f32 v[48:49], v[4:5], v[8:9] op_sel_hi:[1,0]
	v_pk_mul_f32 v[4:5], v[2:3], v[8:9] op_sel_hi:[1,0]
	v_cvt_pk_bf16_f32 v2, v56, v57
	v_cvt_pk_bf16_f32 v3, v54, v55
	v_cvt_pk_bf16_f32 v4, v4, v5
	v_cvt_pk_bf16_f32 v5, v48, v49
	v_add_u32_e32 v51, s4, v171
	global_store_dwordx4 v[6:7], v[2:5], off offset:256
	s_nop 1
	ds_read_b128 v[2:5], v51
	v_lshlrev_b64 v[48:49], 12, v[52:53]
	s_waitcnt lgkmcnt(0)
	v_mov_b32_e32 v6, v3
	v_mov_b32_e32 v7, v4
	v_mov_b32_e32 v3, v5
	v_pk_add_f32 v[2:3], v[6:7], v[2:3]
	s_nop 0
	v_add_f32_e32 v2, v2, v3
	v_fmamk_f32 v2, v2, 0x3c000000, v243
	v_rsq_f32_e32 v2, v2
	s_nop 0
	v_mul_f32_e32 v50, 0x3dd53b94, v2
	v_pk_mul_f32 v[4:5], v[44:45], v[218:219]
	v_pk_mul_f32 v[6:7], v[42:43], v[212:213]
	v_pk_mul_f32 v[2:3], v[46:47], v[216:217]
	v_pk_mul_f32 v[6:7], v[6:7], v[50:51] op_sel_hi:[1,0]
	v_pk_mul_f32 v[8:9], v[40:41], v[214:215]
	v_pk_mul_f32 v[40:41], v[4:5], v[50:51] op_sel_hi:[1,0]
	v_pk_mul_f32 v[4:5], v[2:3], v[50:51] op_sel_hi:[1,0]
	v_cvt_pk_bf16_f32 v2, v6, v7
	v_lshl_add_u64 v[6:7], s[44:45], 0, v[48:49]
	v_pk_mul_f32 v[8:9], v[8:9], v[50:51] op_sel_hi:[1,0]
	v_lshl_add_u64 v[6:7], v[6:7], 0, s[68:69]
	v_cvt_pk_bf16_f32 v3, v8, v9
	v_cvt_pk_bf16_f32 v4, v4, v5
	v_cvt_pk_bf16_f32 v5, v40, v41
	v_lshl_add_u64 v[6:7], v[6:7], 0, v[38:39]
	global_store_dwordx4 v[6:7], v[2:5], off
	s_nop 1
	ds_read_b128 v[2:5], v51 offset:16
	s_waitcnt lgkmcnt(0)
	v_mov_b32_e32 v8, v3
	v_mov_b32_e32 v9, v4
	v_mov_b32_e32 v3, v5
	v_pk_add_f32 v[2:3], v[8:9], v[2:3]
	s_nop 0
	v_add_f32_e32 v2, v2, v3
	v_fmamk_f32 v2, v2, 0x3c000000, v243
	v_rsq_f32_e32 v2, v2
	s_nop 0
	v_mul_f32_e32 v8, 0x3dd53b94, v2
	v_pk_mul_f32 v[4:5], v[28:29], v[218:219]
	v_pk_mul_f32 v[34:35], v[34:35], v[214:215]
	v_pk_mul_f32 v[36:37], v[36:37], v[212:213]
	v_pk_mul_f32 v[2:3], v[30:31], v[216:217]
	v_pk_mul_f32 v[34:35], v[34:35], v[8:9] op_sel_hi:[1,0]
	v_pk_mul_f32 v[36:37], v[36:37], v[8:9] op_sel_hi:[1,0]
	v_pk_mul_f32 v[28:29], v[4:5], v[8:9] op_sel_hi:[1,0]
	v_pk_mul_f32 v[4:5], v[2:3], v[8:9] op_sel_hi:[1,0]
	v_cvt_pk_bf16_f32 v2, v36, v37
	v_cvt_pk_bf16_f32 v3, v34, v35
	v_cvt_pk_bf16_f32 v4, v4, v5
	v_cvt_pk_bf16_f32 v5, v28, v29
	v_add_u32_e32 v31, s4, v170
	global_store_dwordx4 v[6:7], v[2:5], off offset:256
	s_nop 1
	ds_read_b128 v[2:5], v31
	v_lshlrev_b64 v[28:29], 12, v[32:33]
	s_waitcnt lgkmcnt(0)
	v_mov_b32_e32 v6, v3
	v_mov_b32_e32 v7, v4
	v_mov_b32_e32 v3, v5
	v_pk_add_f32 v[2:3], v[6:7], v[2:3]
	s_nop 0
	v_add_f32_e32 v2, v2, v3
	v_fmamk_f32 v2, v2, 0x3c000000, v243
	v_rsq_f32_e32 v2, v2
	s_nop 0
	v_mul_f32_e32 v30, 0x3dd53b94, v2
	v_pk_mul_f32 v[4:5], v[24:25], v[218:219]
	v_pk_mul_f32 v[6:7], v[22:23], v[212:213]
	v_pk_mul_f32 v[2:3], v[26:27], v[216:217]
	v_pk_mul_f32 v[6:7], v[6:7], v[30:31] op_sel_hi:[1,0]
	v_pk_mul_f32 v[8:9], v[20:21], v[214:215]
	v_pk_mul_f32 v[20:21], v[4:5], v[30:31] op_sel_hi:[1,0]
	v_pk_mul_f32 v[4:5], v[2:3], v[30:31] op_sel_hi:[1,0]
	v_cvt_pk_bf16_f32 v2, v6, v7
	v_lshl_add_u64 v[6:7], s[44:45], 0, v[28:29]
	v_pk_mul_f32 v[8:9], v[8:9], v[30:31] op_sel_hi:[1,0]
	v_lshl_add_u64 v[6:7], v[6:7], 0, s[68:69]
	v_cvt_pk_bf16_f32 v3, v8, v9
	v_cvt_pk_bf16_f32 v4, v4, v5
	v_cvt_pk_bf16_f32 v5, v20, v21
	v_lshl_add_u64 v[6:7], v[6:7], 0, v[38:39]
	global_store_dwordx4 v[6:7], v[2:5], off
	s_nop 1
	ds_read_b128 v[2:5], v31 offset:16
	s_waitcnt lgkmcnt(0)
	v_mov_b32_e32 v8, v3
	v_mov_b32_e32 v9, v4
	v_mov_b32_e32 v3, v5
	v_pk_add_f32 v[2:3], v[8:9], v[2:3]
	s_nop 0
	v_add_f32_e32 v2, v2, v3
	v_fmamk_f32 v2, v2, 0x3c000000, v243
	v_rsq_f32_e32 v2, v2
	s_nop 0
	v_mul_f32_e32 v8, 0x3dd53b94, v2
	v_pk_mul_f32 v[4:5], v[10:11], v[218:219]
	v_pk_mul_f32 v[14:15], v[14:15], v[214:215]
	v_pk_mul_f32 v[16:17], v[16:17], v[212:213]
	v_pk_mul_f32 v[2:3], v[12:13], v[216:217]
	v_pk_mul_f32 v[14:15], v[14:15], v[8:9] op_sel_hi:[1,0]
	v_pk_mul_f32 v[16:17], v[16:17], v[8:9] op_sel_hi:[1,0]
	v_pk_mul_f32 v[10:11], v[4:5], v[8:9] op_sel_hi:[1,0]
	v_pk_mul_f32 v[4:5], v[2:3], v[8:9] op_sel_hi:[1,0]
	v_cvt_pk_bf16_f32 v2, v16, v17
	v_cvt_pk_bf16_f32 v3, v14, v15
	v_cvt_pk_bf16_f32 v4, v4, v5
	v_cvt_pk_bf16_f32 v5, v10, v11
	global_store_dwordx4 v[6:7], v[2:5], off offset:256
	s_nop 1
	s_and_b64 vcc, exec, s[40:41]
	s_mov_b64 s[0:1], -1
	s_cbranch_vccnz .LBB0_228

.LBB0_318:
	s_or_b64 exec, exec, s[0:1]
	v_mov_b32_e32 v66, v80
	s_waitcnt lgkmcnt(0)
	v_mov_b32_e32 v67, v80
	v_pk_mul_f32 v[64:65], v[64:65], v[66:67]
	v_pk_mul_f32 v[56:57], v[56:57], v[66:67]
	v_mov_b32_e32 v66, v178
	v_mov_b32_e32 v67, v178
	v_pk_mul_f32 v[60:61], v[60:61], v[66:67]
	v_pk_mul_f32 v[52:53], v[52:53], v[66:67]
	v_mov_b32_e32 v66, v176
	v_mov_b32_e32 v67, v176
	v_pk_mul_f32 v[48:49], v[48:49], v[66:67]
	v_pk_mul_f32 v[44:45], v[44:45], v[66:67]
	v_mov_b32_e32 v66, v174
	v_mov_b32_e32 v67, v174
	v_pk_mul_f32 v[40:41], v[40:41], v[66:67]
	v_pk_mul_f32 v[32:33], v[32:33], v[66:67]
	v_mov_b32_e32 v66, v112
	v_mov_b32_e32 v67, v112
	v_mov_b32_e32 v81, v80
	v_pk_mul_f32 v[36:37], v[36:37], v[66:67]
	v_pk_mul_f32 v[28:29], v[28:29], v[66:67]
	v_mov_b32_e32 v66, v114
	v_mov_b32_e32 v67, v114
	v_mov_b32_e32 v171, v170
	v_pk_mul_f32 v[62:63], v[62:63], v[80:81]
	v_pk_mul_f32 v[54:55], v[54:55], v[80:81]
	v_pk_mul_f32 v[24:25], v[24:25], v[66:67]
	v_pk_mul_f32 v[20:21], v[20:21], v[66:67]
	v_mov_b32_e32 v66, v172
	v_mov_b32_e32 v67, v172
	v_mov_b32_e32 v80, v170
	v_mov_b32_e32 v81, v170
	s_add_i32 s5, 0, 0x20000
	v_pk_mul_f32 v[16:17], v[16:17], v[66:67]
	v_pk_mul_f32 v[12:13], v[12:13], v[66:67]
	v_pk_mul_f32 v[66:67], v[8:9], v[80:81]
	v_pk_mul_f32 v[8:9], v[2:3], v[170:171]
	s_waitcnt lgkmcnt(0)
	s_barrier
	v_lshl_add_u32 v2, v160, 4, s5
	v_pk_mul_f32 v[68:69], v[6:7], v[170:171]
	v_pk_mul_f32 v[6:7], v[4:5], v[80:81]
	ds_read_b128 v[2:5], v2
	v_mov_b32_e32 v115, v114
	v_pk_mul_f32 v[22:23], v[22:23], v[114:115]
	v_pk_mul_f32 v[18:19], v[18:19], v[114:115]
	v_mov_b32_e32 v113, v112
	s_waitcnt lgkmcnt(0)
	v_mov_b32_e32 v114, v3
	v_mov_b32_e32 v115, v4
	v_mov_b32_e32 v3, v5
	v_pk_add_f32 v[2:3], v[114:115], v[2:3]
	v_lshlrev_b32_e32 v80, 3, v183
	v_add_f32_e32 v2, v2, v3
	v_fmamk_f32 v2, v2, 0x3c000000, v243
	v_cmp_gt_f32_e32 vcc, s37, v2
	v_mul_f32_e32 v3, 0x4f800000, v2
	v_pk_mul_f32 v[34:35], v[34:35], v[112:113]
	v_cndmask_b32_e32 v2, v2, v3, vcc
	v_sqrt_f32_e32 v3, v2
	v_pk_mul_f32 v[26:27], v[26:27], v[112:113]
	v_add_u32_e32 v112, s76, v80
	v_ashrrev_i32_e32 v113, 31, v112
	v_add_u32_e32 v4, -1, v3
	v_fma_f32 v5, -v4, v3, v2
	v_cmp_ge_f32_e64 s[42:43], 0, v5
	v_add_u32_e32 v5, 1, v3
	v_mov_b32_e32 v173, v172
	v_cndmask_b32_e64 v4, v3, v4, s[42:43]
	v_fma_f32 v3, -v5, v3, v2
	v_cmp_lt_f32_e64 s[42:43], 0, v3
	v_mov_b32_e32 v175, v174
	v_pk_mul_f32 v[38:39], v[38:39], v[174:175]
	v_cndmask_b32_e64 v3, v4, v5, s[42:43]
	v_mul_f32_e32 v4, 0x37800000, v3
	v_cndmask_b32_e32 v3, v3, v4, vcc
	v_cmp_class_f32_e32 vcc, v2, v241
	v_pk_mul_f32 v[30:31], v[30:31], v[174:175]
	v_pk_mul_f32 v[14:15], v[14:15], v[172:173]
	v_cndmask_b32_e32 v2, v3, v2, vcc
	v_div_scale_f32 v3, s[6:7], v2, v2, 1.0
	v_rcp_f32_e32 v4, v3
	v_pk_mul_f32 v[10:11], v[10:11], v[172:173]
	s_lshl_b32 s10, s4, 7
	s_lshl_b64 s[0:1], s[64:65], 20
	v_fma_f32 v5, -v3, v4, 1.0
	v_fmac_f32_e32 v4, v5, v4
	v_div_scale_f32 v5, vcc, 1.0, v2, 1.0
	v_mul_f32_e32 v81, v5, v4
	v_fma_f32 v114, -v3, v81, v5
	v_fmac_f32_e32 v81, v114, v4
	v_fma_f32 v3, -v3, v81, v5
	v_div_fmas_f32 v3, v3, v4, v81
	v_lshl_add_u64 v[114:115], v[112:113], 2, s[46:47]
	v_div_fixup_f32 v174, v3, v2, 1.0
	global_load_dwordx4 v[212:215], v[114:115], off
	global_load_dwordx4 v[216:219], v[114:115], off offset:16
	s_ashr_i32 s11, s10, 31
	v_readlane_b32 s6, v251, 43
	v_readlane_b32 s7, v251, 44
	s_add_u32 s0, s6, s0
	s_addc_u32 s1, s7, s1
	v_lshlrev_b64 v[160:161], 12, v[160:161]
	v_lshl_add_u64 v[160:161], s[0:1], 0, v[160:161]
	s_lshl_b64 s[10:11], s[10:11], 1
	v_lshl_add_u64 v[160:161], v[160:161], 0, s[10:11]
	v_lshlrev_b64 v[112:113], 1, v[112:113]
	v_lshl_add_u64 v[160:161], v[160:161], 0, v[112:113]
	v_cvt_pk_bf16_f32 v8, v8, v9
	v_cvt_pk_bf16_f32 v14, v14, v15
	v_cvt_pk_bf16_f32 v10, v10, v11
	v_cvt_pk_bf16_f32 v15, v16, v17
	v_cvt_pk_bf16_f32 v11, v12, v13
	v_mov_b32_e32 v177, v176
	v_pk_mul_f32 v[46:47], v[46:47], v[176:177]
	v_mov_b32_e32 v179, v178
	v_pk_mul_f32 v[42:43], v[42:43], v[176:177]
	v_pk_mul_f32 v[58:59], v[58:59], v[178:179]
	v_pk_mul_f32 v[50:51], v[50:51], v[178:179]
	s_waitcnt vmcnt(0)
	v_pk_mul_f32 v[4:5], v[166:167], v[218:219]
	v_pk_mul_f32 v[162:163], v[162:163], v[214:215]
	v_pk_mul_f32 v[164:165], v[164:165], v[212:213]
	v_pk_mul_f32 v[2:3], v[168:169], v[216:217]
	v_pk_mul_f32 v[162:163], v[162:163], v[174:175] op_sel_hi:[1,0]
	v_pk_mul_f32 v[164:165], v[164:165], v[174:175] op_sel_hi:[1,0]
	v_pk_mul_f32 v[166:167], v[4:5], v[174:175] op_sel_hi:[1,0]
	v_pk_mul_f32 v[4:5], v[2:3], v[174:175] op_sel_hi:[1,0]
	v_cvt_pk_bf16_f32 v2, v164, v165
	v_cvt_pk_bf16_f32 v3, v162, v163
	v_cvt_pk_bf16_f32 v4, v4, v5
	v_cvt_pk_bf16_f32 v5, v166, v167
	global_store_dwordx4 v[160:161], v[2:5], off
	s_nop 1
	s_nop 1
	v_lshl_add_u32 v2, v150, 4, s5
	ds_read_b128 v[2:5], v2
	v_lshlrev_b64 v[150:151], 12, v[150:151]
	v_lshl_add_u64 v[150:151], s[0:1], 0, v[150:151]
	v_lshl_add_u64 v[150:151], v[150:151], 0, s[10:11]
	v_lshl_add_u64 v[150:151], v[150:151], 0, v[112:113]
	s_waitcnt lgkmcnt(0)
	v_mov_b32_e32 v160, v3
	v_mov_b32_e32 v161, v4
	v_mov_b32_e32 v3, v5
	v_pk_add_f32 v[2:3], v[160:161], v[2:3]
	s_nop 0
	v_add_f32_e32 v2, v2, v3
	v_fmamk_f32 v2, v2, 0x3c000000, v243
	v_rsq_f32_e32 v164, v2
	s_nop 0
	v_pk_mul_f32 v[4:5], v[156:157], v[218:219]
	v_pk_mul_f32 v[152:153], v[152:153], v[214:215]
	v_pk_mul_f32 v[154:155], v[154:155], v[212:213]
	v_pk_mul_f32 v[2:3], v[158:159], v[216:217]
	v_pk_mul_f32 v[152:153], v[152:153], v[164:165] op_sel_hi:[1,0]
	v_pk_mul_f32 v[154:155], v[154:155], v[164:165] op_sel_hi:[1,0]
	v_pk_mul_f32 v[156:157], v[4:5], v[164:165] op_sel_hi:[1,0]
	v_pk_mul_f32 v[4:5], v[2:3], v[164:165] op_sel_hi:[1,0]
	v_cvt_pk_bf16_f32 v2, v154, v155
	v_cvt_pk_bf16_f32 v3, v152, v153
	v_cvt_pk_bf16_f32 v4, v4, v5
	v_cvt_pk_bf16_f32 v5, v156, v157
	global_store_dwordx4 v[150:151], v[2:5], off
	s_nop 1
	s_nop 1
	v_lshl_add_u32 v2, v126, 4, s5
	ds_read_b128 v[2:5], v2
	v_lshlrev_b64 v[126:127], 12, v[126:127]
	v_lshl_add_u64 v[126:127], s[0:1], 0, v[126:127]
	v_lshl_add_u64 v[126:127], v[126:127], 0, s[10:11]
	v_lshl_add_u64 v[126:127], v[126:127], 0, v[112:113]
	s_waitcnt lgkmcnt(0)
	v_mov_b32_e32 v150, v3
	v_mov_b32_e32 v151, v4
	v_mov_b32_e32 v3, v5
	v_pk_add_f32 v[2:3], v[150:151], v[2:3]
	s_nop 0
	v_add_f32_e32 v2, v2, v3
	v_fmamk_f32 v2, v2, 0x3c000000, v243
	v_rsq_f32_e32 v150, v2
	s_nop 0
	v_pk_mul_f32 v[4:5], v[146:147], v[218:219]
	v_pk_mul_f32 v[128:129], v[128:129], v[214:215]
	v_pk_mul_f32 v[144:145], v[144:145], v[212:213]
	v_pk_mul_f32 v[2:3], v[148:149], v[216:217]
	v_pk_mul_f32 v[128:129], v[128:129], v[150:151] op_sel_hi:[1,0]
	v_pk_mul_f32 v[144:145], v[144:145], v[150:151] op_sel_hi:[1,0]
	v_pk_mul_f32 v[146:147], v[4:5], v[150:151] op_sel_hi:[1,0]
	v_pk_mul_f32 v[4:5], v[2:3], v[150:151] op_sel_hi:[1,0]
	v_cvt_pk_bf16_f32 v2, v144, v145
	v_cvt_pk_bf16_f32 v3, v128, v129
	v_cvt_pk_bf16_f32 v4, v4, v5
	v_cvt_pk_bf16_f32 v5, v146, v147
	global_store_dwordx4 v[126:127], v[2:5], off
	s_nop 1
	s_nop 1
	v_lshl_add_u32 v2, v116, 4, s5
	ds_read_b128 v[2:5], v2
	v_lshlrev_b64 v[116:117], 12, v[116:117]
	v_lshl_add_u64 v[116:117], s[0:1], 0, v[116:117]
	v_lshl_add_u64 v[116:117], v[116:117], 0, s[10:11]
	v_lshl_add_u64 v[116:117], v[116:117], 0, v[112:113]
	s_waitcnt lgkmcnt(0)
	v_mov_b32_e32 v126, v3
	v_mov_b32_e32 v127, v4
	v_mov_b32_e32 v3, v5
	v_pk_add_f32 v[2:3], v[126:127], v[2:3]
	s_nop 0
	v_add_f32_e32 v2, v2, v3
	v_fmamk_f32 v2, v2, 0x3c000000, v243
	v_rsq_f32_e32 v144, v2
	s_nop 0
	v_pk_mul_f32 v[4:5], v[122:123], v[218:219]
	v_pk_mul_f32 v[118:119], v[118:119], v[214:215]
	v_pk_mul_f32 v[120:121], v[120:121], v[212:213]
	v_pk_mul_f32 v[2:3], v[124:125], v[216:217]
	v_pk_mul_f32 v[118:119], v[118:119], v[144:145] op_sel_hi:[1,0]
	v_pk_mul_f32 v[120:121], v[120:121], v[144:145] op_sel_hi:[1,0]
	v_pk_mul_f32 v[122:123], v[4:5], v[144:145] op_sel_hi:[1,0]
	v_pk_mul_f32 v[4:5], v[2:3], v[144:145] op_sel_hi:[1,0]
	v_cvt_pk_bf16_f32 v2, v120, v121
	v_cvt_pk_bf16_f32 v3, v118, v119
	v_cvt_pk_bf16_f32 v4, v4, v5
	v_cvt_pk_bf16_f32 v5, v122, v123
	global_store_dwordx4 v[116:117], v[2:5], off
	s_nop 1
	s_nop 1
	v_lshl_add_u32 v2, v98, 4, s5
	ds_read_b128 v[2:5], v2
	v_lshlrev_b64 v[98:99], 12, v[98:99]
	v_lshl_add_u64 v[98:99], s[0:1], 0, v[98:99]
	v_lshl_add_u64 v[98:99], v[98:99], 0, s[10:11]
	v_lshl_add_u64 v[98:99], v[98:99], 0, v[112:113]
	s_waitcnt lgkmcnt(0)
	v_mov_b32_e32 v116, v3
	v_mov_b32_e32 v117, v4
	v_mov_b32_e32 v3, v5
	v_pk_add_f32 v[2:3], v[116:117], v[2:3]
	s_nop 0
	v_add_f32_e32 v2, v2, v3
	v_fmamk_f32 v2, v2, 0x3c000000, v243
	v_rsq_f32_e32 v116, v2
	s_nop 0
	v_pk_mul_f32 v[4:5], v[108:109], v[218:219]
	v_pk_mul_f32 v[104:105], v[104:105], v[214:215]
	v_pk_mul_f32 v[106:107], v[106:107], v[212:213]
	v_pk_mul_f32 v[2:3], v[110:111], v[216:217]
	v_pk_mul_f32 v[104:105], v[104:105], v[116:117] op_sel_hi:[1,0]
	v_pk_mul_f32 v[106:107], v[106:107], v[116:117] op_sel_hi:[1,0]
	v_pk_mul_f32 v[108:109], v[4:5], v[116:117] op_sel_hi:[1,0]
	v_pk_mul_f32 v[4:5], v[2:3], v[116:117] op_sel_hi:[1,0]
	v_cvt_pk_bf16_f32 v2, v106, v107
	v_cvt_pk_bf16_f32 v3, v104, v105
	v_cvt_pk_bf16_f32 v4, v4, v5
	v_cvt_pk_bf16_f32 v5, v108, v109
	global_store_dwordx4 v[98:99], v[2:5], off
	s_nop 1
	s_nop 1
	v_lshl_add_u32 v2, v90, 4, s5
	ds_read_b128 v[2:5], v2
	v_lshlrev_b64 v[90:91], 12, v[90:91]
	v_lshl_add_u64 v[90:91], s[0:1], 0, v[90:91]
	v_lshl_add_u64 v[90:91], v[90:91], 0, s[10:11]
	v_lshl_add_u64 v[90:91], v[90:91], 0, v[112:113]
	s_waitcnt lgkmcnt(0)
	v_mov_b32_e32 v98, v3
	v_mov_b32_e32 v99, v4
	v_mov_b32_e32 v3, v5
	v_pk_add_f32 v[2:3], v[98:99], v[2:3]
	s_nop 0
	v_add_f32_e32 v2, v2, v3
	v_fmamk_f32 v2, v2, 0x3c000000, v243
	v_rsq_f32_e32 v98, v2
	s_nop 0
	v_pk_mul_f32 v[4:5], v[100:101], v[218:219]
	v_pk_mul_f32 v[94:95], v[94:95], v[214:215]
	v_pk_mul_f32 v[96:97], v[96:97], v[212:213]
	v_pk_mul_f32 v[2:3], v[102:103], v[216:217]
	v_pk_mul_f32 v[94:95], v[94:95], v[98:99] op_sel_hi:[1,0]
	v_pk_mul_f32 v[96:97], v[96:97], v[98:99] op_sel_hi:[1,0]
	v_pk_mul_f32 v[100:101], v[4:5], v[98:99] op_sel_hi:[1,0]
	v_pk_mul_f32 v[4:5], v[2:3], v[98:99] op_sel_hi:[1,0]
	v_cvt_pk_bf16_f32 v2, v96, v97
	v_cvt_pk_bf16_f32 v3, v94, v95
	v_cvt_pk_bf16_f32 v4, v4, v5
	v_cvt_pk_bf16_f32 v5, v100, v101
	global_store_dwordx4 v[90:91], v[2:5], off
	s_nop 1
	s_nop 1
	v_lshl_add_u32 v2, v82, 4, s5
	ds_read_b128 v[2:5], v2
	v_lshlrev_b64 v[82:83], 12, v[82:83]
	v_lshl_add_u64 v[82:83], s[0:1], 0, v[82:83]
	v_lshl_add_u64 v[82:83], v[82:83], 0, s[10:11]
	v_lshl_add_u64 v[82:83], v[82:83], 0, v[112:113]
	s_waitcnt lgkmcnt(0)
	v_mov_b32_e32 v90, v3
	v_mov_b32_e32 v91, v4
	v_mov_b32_e32 v3, v5
	v_pk_add_f32 v[2:3], v[90:91], v[2:3]
	s_nop 0
	v_add_f32_e32 v2, v2, v3
	v_fmamk_f32 v2, v2, 0x3c000000, v243
	v_rsq_f32_e32 v90, v2
	s_nop 0
	v_pk_mul_f32 v[4:5], v[88:89], v[218:219]
	v_pk_mul_f32 v[84:85], v[84:85], v[214:215]
	v_pk_mul_f32 v[86:87], v[86:87], v[212:213]
	v_pk_mul_f32 v[2:3], v[92:93], v[216:217]
	v_pk_mul_f32 v[84:85], v[84:85], v[90:91] op_sel_hi:[1,0]
	v_pk_mul_f32 v[86:87], v[86:87], v[90:91] op_sel_hi:[1,0]
	v_pk_mul_f32 v[88:89], v[4:5], v[90:91] op_sel_hi:[1,0]
	v_pk_mul_f32 v[4:5], v[2:3], v[90:91] op_sel_hi:[1,0]
	v_cvt_pk_bf16_f32 v2, v86, v87
	v_cvt_pk_bf16_f32 v3, v84, v85
	v_cvt_pk_bf16_f32 v4, v4, v5
	v_cvt_pk_bf16_f32 v5, v88, v89
	global_store_dwordx4 v[82:83], v[2:5], off
	s_nop 1
	s_nop 1
	v_add_u32_e32 v2, s5, v143
	ds_read_b128 v[2:5], v2
	v_ashrrev_i32_e32 v143, 31, v142
	s_waitcnt lgkmcnt(0)
	v_mov_b32_e32 v82, v3
	v_mov_b32_e32 v83, v4
	v_mov_b32_e32 v3, v5
	v_pk_add_f32 v[2:3], v[82:83], v[2:3]
	s_nop 0
	v_add_f32_e32 v2, v2, v3
	v_fmamk_f32 v2, v2, 0x3c000000, v243
	v_rsq_f32_e32 v86, v2
	s_nop 0
	v_ashrrev_i32_e32 v81, 31, v80
	v_pk_mul_f32 v[4:5], v[76:77], v[218:219]
	v_pk_mul_f32 v[70:71], v[70:71], v[212:213]
	v_pk_mul_f32 v[2:3], v[78:79], v[216:217]
	v_pk_mul_f32 v[70:71], v[70:71], v[86:87] op_sel_hi:[1,0]
	v_pk_mul_f32 v[76:77], v[4:5], v[86:87] op_sel_hi:[1,0]
	v_pk_mul_f32 v[4:5], v[2:3], v[86:87] op_sel_hi:[1,0]
	v_cvt_pk_bf16_f32 v2, v70, v71
	v_lshlrev_b64 v[70:71], 12, v[74:75]
	v_pk_mul_f32 v[72:73], v[72:73], v[214:215]
	v_lshl_add_u64 v[70:71], s[0:1], 0, v[70:71]
	s_lshl_b64 s[0:1], s[64:65], 8
	v_pk_mul_f32 v[72:73], v[72:73], v[86:87] op_sel_hi:[1,0]
	v_lshl_add_u64 v[70:71], v[70:71], 0, s[10:11]
	s_add_u32 s0, s0, s68
	v_cvt_pk_bf16_f32 v3, v72, v73
	v_cvt_pk_bf16_f32 v4, v4, v5
	v_cvt_pk_bf16_f32 v5, v76, v77
	v_lshl_add_u64 v[70:71], v[70:71], 0, v[112:113]
	s_addc_u32 s1, s1, s70
	global_store_dwordx4 v[70:71], v[2:5], off
	s_nop 1
	v_lshl_add_u64 v[70:71], v[80:81], 0, s[76:77]
	v_lshlrev_b64 v[70:71], 13, v[70:71]
	v_lshl_add_u64 v[2:3], s[0:1], 0, v[142:143]
	v_alignbit_b32 v3, v3, v2, 8
	v_and_b32_e32 v3, -16, v3
	v_add_u32_e32 v4, s4, v3
	v_ashrrev_i32_e32 v5, 31, v4
	v_readlane_b32 s0, v251, 51
	v_lshlrev_b64 v[4:5], 20, v[4:5]
	v_readlane_b32 s1, v251, 52
	v_and_b32_e32 v72, 0xff0, v2
	v_and_b32_e32 v73, 3, v142
	v_lshl_add_u64 v[4:5], s[0:1], 0, v[4:5]
	v_lshl_add_u64 v[4:5], v[4:5], 0, v[70:71]
	v_lshlrev_b32_e32 v70, 1, v72
	v_mov_b32_e32 v71, v0
	v_lshl_add_u64 v[4:5], v[4:5], 0, v[70:71]
	v_and_b32_e32 v70, 8, v142
	v_lshl_add_u64 v[4:5], v[4:5], 0, v[70:71]
	v_lshlrev_b32_e32 v70, 1, v73
	v_lshlrev_b32_e32 v2, 2, v2
	v_lshl_add_u64 v[4:5], v[4:5], 0, v[70:71]
	v_and_b32_e32 v2, 16, v2
	v_mov_b32_e32 v3, v0
	v_lshl_add_u64 v[70:71], v[4:5], 0, v[2:3]
	s_movk_i32 s0, 0x2000
	v_cvt_pk_bf16_f32 v3, v66, v67
	v_add_co_u32_e32 v66, vcc, s0, v70
	s_movk_i32 s0, 0x4000
	s_nop 0
	v_addc_co_u32_e32 v67, vcc, 0, v71, vcc
	v_cvt_pk_bf16_f32 v2, v68, v69
	v_add_co_u32_e32 v68, vcc, s0, v70
	s_movk_i32 s0, 0x6000
	s_nop 0
	v_addc_co_u32_e32 v69, vcc, 0, v71, vcc
	v_add_co_u32_e32 v72, vcc, s0, v70
	s_mov_b32 s0, 0x8000
	s_nop 0
	v_addc_co_u32_e32 v73, vcc, 0, v71, vcc
	global_store_short v[70:71], v2, off
	global_store_short_d16_hi v[66:67], v2, off
	v_add_co_u32_e32 v2, vcc, s0, v70
	global_store_short v[68:69], v3, off
	global_store_short_d16_hi v[72:73], v3, off
	v_addc_co_u32_e32 v3, vcc, 0, v71, vcc
	s_mov_b32 s0, 0xa000
	v_add_co_u32_e32 v4, vcc, s0, v70
	s_mov_b32 s0, 0xc000
	s_nop 0
	v_addc_co_u32_e32 v5, vcc, 0, v71, vcc
	v_cvt_pk_bf16_f32 v74, v6, v7
	v_add_co_u32_e32 v6, vcc, s0, v70
	s_mov_b32 s0, 0xe000
	s_nop 0
	v_addc_co_u32_e32 v7, vcc, 0, v71, vcc
	global_store_short v[2:3], v8, off
	global_store_short_d16_hi v[4:5], v8, off
	v_add_co_u32_e32 v8, vcc, s0, v70
	global_store_short v[6:7], v74, off
	s_nop 0
	v_addc_co_u32_e32 v9, vcc, 0, v71, vcc
	global_store_short_d16_hi v[8:9], v74, off
	global_store_short v[70:71], v14, off offset:32
	global_store_short_d16_hi v[66:67], v14, off offset:32
	global_store_short v[68:69], v15, off offset:32
	global_store_short_d16_hi v[72:73], v15, off offset:32
	global_store_short v[2:3], v10, off offset:32
	global_store_short_d16_hi v[4:5], v10, off offset:32
	global_store_short v[6:7], v11, off offset:32
	global_store_short_d16_hi v[8:9], v11, off offset:32
	v_cvt_pk_bf16_f32 v10, v22, v23
	v_cvt_pk_bf16_f32 v11, v24, v25
	global_store_short v[70:71], v10, off offset:64
	global_store_short_d16_hi v[66:67], v10, off offset:64
	global_store_short v[68:69], v11, off offset:64
	global_store_short_d16_hi v[72:73], v11, off offset:64
	v_cvt_pk_bf16_f32 v10, v18, v19
	v_cvt_pk_bf16_f32 v11, v20, v21
	global_store_short v[2:3], v10, off offset:64
	global_store_short_d16_hi v[4:5], v10, off offset:64
	global_store_short v[6:7], v11, off offset:64
	global_store_short_d16_hi v[8:9], v11, off offset:64
	v_cvt_pk_bf16_f32 v10, v34, v35
	v_cvt_pk_bf16_f32 v11, v36, v37
	global_store_short v[70:71], v10, off offset:96
	global_store_short_d16_hi v[66:67], v10, off offset:96
	global_store_short v[68:69], v11, off offset:96
	global_store_short_d16_hi v[72:73], v11, off offset:96
	v_cvt_pk_bf16_f32 v10, v26, v27
	v_cvt_pk_bf16_f32 v11, v28, v29
	global_store_short v[2:3], v10, off offset:96
	global_store_short_d16_hi v[4:5], v10, off offset:96
	global_store_short v[6:7], v11, off offset:96
	global_store_short_d16_hi v[8:9], v11, off offset:96
	v_cvt_pk_bf16_f32 v10, v38, v39
	v_cvt_pk_bf16_f32 v11, v40, v41
	global_store_short v[70:71], v10, off offset:256
	global_store_short_d16_hi v[66:67], v10, off offset:256
	global_store_short v[68:69], v11, off offset:256
	global_store_short_d16_hi v[72:73], v11, off offset:256
	v_cvt_pk_bf16_f32 v10, v30, v31
	v_cvt_pk_bf16_f32 v11, v32, v33
	global_store_short v[2:3], v10, off offset:256
	global_store_short_d16_hi v[4:5], v10, off offset:256
	global_store_short v[6:7], v11, off offset:256
	global_store_short_d16_hi v[8:9], v11, off offset:256
	v_cvt_pk_bf16_f32 v10, v46, v47
	v_cvt_pk_bf16_f32 v11, v48, v49
	global_store_short v[70:71], v10, off offset:288
	global_store_short_d16_hi v[66:67], v10, off offset:288
	global_store_short v[68:69], v11, off offset:288
	global_store_short_d16_hi v[72:73], v11, off offset:288
	v_cvt_pk_bf16_f32 v10, v42, v43
	v_cvt_pk_bf16_f32 v11, v44, v45
	global_store_short v[2:3], v10, off offset:288
	global_store_short_d16_hi v[4:5], v10, off offset:288
	global_store_short v[6:7], v11, off offset:288
	global_store_short_d16_hi v[8:9], v11, off offset:288
	v_cvt_pk_bf16_f32 v10, v58, v59
	v_cvt_pk_bf16_f32 v11, v60, v61
	global_store_short v[70:71], v10, off offset:320
	global_store_short_d16_hi v[66:67], v10, off offset:320
	global_store_short v[68:69], v11, off offset:320
	global_store_short_d16_hi v[72:73], v11, off offset:320
	v_cvt_pk_bf16_f32 v10, v50, v51
	v_cvt_pk_bf16_f32 v11, v52, v53
	global_store_short v[2:3], v10, off offset:320
	global_store_short_d16_hi v[4:5], v10, off offset:320
	global_store_short v[6:7], v11, off offset:320
	global_store_short_d16_hi v[8:9], v11, off offset:320
	v_cvt_pk_bf16_f32 v10, v62, v63
	v_cvt_pk_bf16_f32 v11, v64, v65
	global_store_short v[70:71], v10, off offset:352
	global_store_short_d16_hi v[66:67], v10, off offset:352
	global_store_short v[68:69], v11, off offset:352
	global_store_short_d16_hi v[72:73], v11, off offset:352
	v_cvt_pk_bf16_f32 v10, v54, v55
	s_mov_b64 s[0:1], -1
	s_and_b64 vcc, exec, s[40:41]
	v_cvt_pk_bf16_f32 v11, v56, v57
	global_store_short v[2:3], v10, off offset:352
	global_store_short_d16_hi v[4:5], v10, off offset:352
	global_store_short v[6:7], v11, off offset:352
	global_store_short_d16_hi v[8:9], v11, off offset:352
	s_cbranch_vccnz .LBB0_286
	s_andn2_b64 vcc, exec, s[54:55]
	s_cbranch_vccnz .LBB0_285
	s_barrier
	s_branch .LBB0_285
